# v9
# baseline (speedup 1.0000x reference)
.LBB0_948:
	s_or_b64 exec, exec, s[8:9]
	s_waitcnt lgkmcnt(0)
	v_add_u32_e32 v72, v181, v176
	ds_read_b128 v[64:67], v72
	ds_read_b128 v[68:71], v72 offset:32
	s_add_u32 s8, s88, s14
	s_addc_u32 s9, s89, s15
	s_lshl_b64 s[6:7], s[12:13], 1
	s_waitcnt lgkmcnt(1)
	v_rcp_f32_e32 v73, v64
	v_rcp_f32_e32 v74, v65
	v_rcp_f32_e32 v75, v66
	v_rcp_f32_e32 v76, v67
	ds_read_b128 v[64:67], v72 offset:64
	s_add_u32 s6, s8, s6
	v_ashrrev_i32_e32 v181, 31, v180
	s_addc_u32 s7, s9, s7
	s_waitcnt lgkmcnt(1)
	v_rcp_f32_e32 v77, v68
	v_rcp_f32_e32 v78, v69
	v_rcp_f32_e32 v79, v70
	v_rcp_f32_e32 v80, v71
	ds_read_b128 v[68:71], v72 offset:96
	s_waitcnt lgkmcnt(1)
	v_rcp_f32_e32 v72, v64
	v_rcp_f32_e32 v81, v65
	v_lshlrev_b64 v[64:65], 12, v[180:181]
	v_lshl_add_u64 v[64:65], s[6:7], 0, v[64:65]
	v_lshlrev_b32_e32 v178, 1, v177
	v_rcp_f32_e32 v82, v66
	v_rcp_f32_e32 v83, v67
	v_lshlrev_b32_e32 v66, 14, v190
	v_lshl_add_u64 v[64:65], v[64:65], 0, v[178:179]
	v_mov_b32_e32 v67, v179
	v_lshl_add_u64 v[64:65], v[64:65], 0, v[66:67]
	s_mov_b64 s[6:7], 0xc4dbb00
	v_lshl_add_u64 v[66:67], v[64:65], 0, s[6:7]
	s_mov_b32 s6, 0xc4db000
	s_waitcnt lgkmcnt(0)
	v_rcp_f32_e32 v84, v68
	v_mul_f32_e32 v0, v0, v73
	v_add_co_u32_e32 v68, vcc, s6, v64
	v_rcp_f32_e32 v85, v69
	v_cvt_pk_bf16_f32 v0, v0, v179
	s_nop 0
	v_addc_co_u32_e32 v69, vcc, 0, v65, vcc
	global_store_short v[68:69], v0, off offset:2816
	v_mul_f32_e32 v0, v48, v73
	v_cvt_pk_bf16_f32 v0, v0, v179
	global_store_short v[66:67], v0, off offset:64
	v_mul_f32_e32 v0, v32, v73
	v_cvt_pk_bf16_f32 v0, v0, v179
	global_store_short v[66:67], v0, off offset:128
	v_mul_f32_e32 v0, v16, v73
	v_cvt_pk_bf16_f32 v0, v0, v179
	global_store_short v[66:67], v0, off offset:192
	v_mul_f32_e32 v0, v1, v74
	s_mov_b32 s6, 0xc4dc000
	v_cvt_pk_bf16_f32 v16, v0, v179
	v_add_co_u32_e32 v0, vcc, s6, v64
	s_mov_b32 s6, 0xc4dd000
	s_nop 0
	v_addc_co_u32_e32 v1, vcc, 0, v65, vcc
	global_store_short v[0:1], v16, off offset:2816
	v_mul_f32_e32 v16, v49, v74
	v_cvt_pk_bf16_f32 v16, v16, v179
	global_store_short v[0:1], v16, off offset:2880
	v_mul_f32_e32 v16, v33, v74
	v_cvt_pk_bf16_f32 v16, v16, v179
	global_store_short v[0:1], v16, off offset:2944
	v_mul_f32_e32 v16, v17, v74
	v_cvt_pk_bf16_f32 v16, v16, v179
	global_store_short v[0:1], v16, off offset:3008
	v_mul_f32_e32 v0, v2, v75
	v_cvt_pk_bf16_f32 v2, v0, v179
	v_add_co_u32_e32 v0, vcc, s6, v64
	s_mov_b32 s6, 0xc4de000
	s_nop 0
	v_addc_co_u32_e32 v1, vcc, 0, v65, vcc
	global_store_short v[0:1], v2, off offset:2816
	v_mul_f32_e32 v2, v50, v75
	v_cvt_pk_bf16_f32 v2, v2, v179
	global_store_short v[0:1], v2, off offset:2880
	v_mul_f32_e32 v2, v34, v75
	v_cvt_pk_bf16_f32 v2, v2, v179
	global_store_short v[0:1], v2, off offset:2944
	v_mul_f32_e32 v2, v18, v75
	v_cvt_pk_bf16_f32 v2, v2, v179
	global_store_short v[0:1], v2, off offset:3008
	v_mul_f32_e32 v0, v3, v76
	v_cvt_pk_bf16_f32 v2, v0, v179
	v_add_co_u32_e32 v0, vcc, s6, v64
	s_mov_b32 s6, 0xc4e3000
	s_nop 0
	v_addc_co_u32_e32 v1, vcc, 0, v65, vcc
	global_store_short v[0:1], v2, off offset:2816
	v_mul_f32_e32 v2, v51, v76
	v_cvt_pk_bf16_f32 v2, v2, v179
	global_store_short v[0:1], v2, off offset:2880
	v_mul_f32_e32 v2, v35, v76
	v_cvt_pk_bf16_f32 v2, v2, v179
	global_store_short v[0:1], v2, off offset:2944
	v_mul_f32_e32 v2, v19, v76
	v_cvt_pk_bf16_f32 v2, v2, v179
	global_store_short v[0:1], v2, off offset:3008
	v_mul_f32_e32 v0, v4, v77
	v_cvt_pk_bf16_f32 v2, v0, v179
	v_add_co_u32_e32 v0, vcc, s6, v64
	s_mov_b32 s6, 0xc4e4000
	s_nop 0
	v_addc_co_u32_e32 v1, vcc, 0, v65, vcc
	global_store_short v[0:1], v2, off offset:2816
	v_mul_f32_e32 v2, v52, v77
	v_cvt_pk_bf16_f32 v2, v2, v179
	global_store_short v[0:1], v2, off offset:2880
	v_mul_f32_e32 v2, v36, v77
	v_cvt_pk_bf16_f32 v2, v2, v179
	global_store_short v[0:1], v2, off offset:2944
	v_mul_f32_e32 v2, v20, v77
	v_cvt_pk_bf16_f32 v2, v2, v179
	global_store_short v[0:1], v2, off offset:3008
	v_mul_f32_e32 v0, v5, v78
	v_cvt_pk_bf16_f32 v2, v0, v179
	v_add_co_u32_e32 v0, vcc, s6, v64
	s_mov_b32 s6, 0xc4e5000
	s_nop 0
	v_addc_co_u32_e32 v1, vcc, 0, v65, vcc
	global_store_short v[0:1], v2, off offset:2816
	v_mul_f32_e32 v2, v53, v78
	v_cvt_pk_bf16_f32 v2, v2, v179
	global_store_short v[0:1], v2, off offset:2880
	v_mul_f32_e32 v2, v37, v78
	v_cvt_pk_bf16_f32 v2, v2, v179
	global_store_short v[0:1], v2, off offset:2944
	v_mul_f32_e32 v2, v21, v78
	v_cvt_pk_bf16_f32 v2, v2, v179
	global_store_short v[0:1], v2, off offset:3008
	v_mul_f32_e32 v0, v6, v79
	v_cvt_pk_bf16_f32 v2, v0, v179
	v_add_co_u32_e32 v0, vcc, s6, v64
	s_mov_b32 s6, 0xc4e6000
	s_nop 0
	v_addc_co_u32_e32 v1, vcc, 0, v65, vcc
	global_store_short v[0:1], v2, off offset:2816
	v_mul_f32_e32 v2, v54, v79
	v_cvt_pk_bf16_f32 v2, v2, v179
	global_store_short v[0:1], v2, off offset:2880
	v_mul_f32_e32 v2, v38, v79
	v_cvt_pk_bf16_f32 v2, v2, v179
	global_store_short v[0:1], v2, off offset:2944
	v_mul_f32_e32 v2, v22, v79
	v_cvt_pk_bf16_f32 v2, v2, v179
	global_store_short v[0:1], v2, off offset:3008
	v_mul_f32_e32 v0, v7, v80
	v_cvt_pk_bf16_f32 v2, v0, v179
	v_add_co_u32_e32 v0, vcc, s6, v64
	s_mov_b32 s6, 0xc4eb000
	s_nop 0
	v_addc_co_u32_e32 v1, vcc, 0, v65, vcc
	global_store_short v[0:1], v2, off offset:2816
	v_mul_f32_e32 v2, v55, v80
	v_cvt_pk_bf16_f32 v2, v2, v179
	global_store_short v[0:1], v2, off offset:2880
	v_mul_f32_e32 v2, v39, v80
	v_cvt_pk_bf16_f32 v2, v2, v179
	global_store_short v[0:1], v2, off offset:2944
	v_mul_f32_e32 v2, v23, v80
	v_cvt_pk_bf16_f32 v2, v2, v179
	global_store_short v[0:1], v2, off offset:3008
	v_mul_f32_e32 v0, v8, v72
	v_cvt_pk_bf16_f32 v2, v0, v179
	v_add_co_u32_e32 v0, vcc, s6, v64
	s_mov_b32 s6, 0xc4ec000
	s_nop 0
	v_addc_co_u32_e32 v1, vcc, 0, v65, vcc
	global_store_short v[0:1], v2, off offset:2816
	v_mul_f32_e32 v2, v56, v72
	v_cvt_pk_bf16_f32 v2, v2, v179
	global_store_short v[0:1], v2, off offset:2880
	v_mul_f32_e32 v2, v40, v72
	v_cvt_pk_bf16_f32 v2, v2, v179
	global_store_short v[0:1], v2, off offset:2944
	v_mul_f32_e32 v2, v24, v72
	v_cvt_pk_bf16_f32 v2, v2, v179
	global_store_short v[0:1], v2, off offset:3008
	v_mul_f32_e32 v0, v9, v81
	v_cvt_pk_bf16_f32 v2, v0, v179
	v_add_co_u32_e32 v0, vcc, s6, v64
	s_mov_b32 s6, 0xc4ed000
	s_nop 0
	v_addc_co_u32_e32 v1, vcc, 0, v65, vcc
	global_store_short v[0:1], v2, off offset:2816
	v_mul_f32_e32 v2, v57, v81
	v_cvt_pk_bf16_f32 v2, v2, v179
	global_store_short v[0:1], v2, off offset:2880
	v_mul_f32_e32 v2, v41, v81
	v_cvt_pk_bf16_f32 v2, v2, v179
	global_store_short v[0:1], v2, off offset:2944
	v_mul_f32_e32 v2, v25, v81
	v_cvt_pk_bf16_f32 v2, v2, v179
	global_store_short v[0:1], v2, off offset:3008
	v_mul_f32_e32 v0, v10, v82
	v_cvt_pk_bf16_f32 v2, v0, v179
	v_add_co_u32_e32 v0, vcc, s6, v64
	s_mov_b32 s6, 0xc4ee000
	s_nop 0
	v_addc_co_u32_e32 v1, vcc, 0, v65, vcc
	global_store_short v[0:1], v2, off offset:2816
	v_mul_f32_e32 v2, v58, v82
	v_cvt_pk_bf16_f32 v2, v2, v179
	global_store_short v[0:1], v2, off offset:2880
	v_mul_f32_e32 v2, v42, v82
	v_cvt_pk_bf16_f32 v2, v2, v179
	global_store_short v[0:1], v2, off offset:2944
	v_mul_f32_e32 v2, v26, v82
	v_cvt_pk_bf16_f32 v2, v2, v179
	global_store_short v[0:1], v2, off offset:3008
	v_mul_f32_e32 v0, v11, v83
	v_cvt_pk_bf16_f32 v2, v0, v179
	v_add_co_u32_e32 v0, vcc, s6, v64
	s_mov_b32 s6, 0xc4f3000
	s_nop 0
	v_addc_co_u32_e32 v1, vcc, 0, v65, vcc
	global_store_short v[0:1], v2, off offset:2816
	v_mul_f32_e32 v2, v59, v83
	v_cvt_pk_bf16_f32 v2, v2, v179
	global_store_short v[0:1], v2, off offset:2880
	v_mul_f32_e32 v2, v43, v83
	v_cvt_pk_bf16_f32 v2, v2, v179
	global_store_short v[0:1], v2, off offset:2944
	v_mul_f32_e32 v2, v27, v83
	v_cvt_pk_bf16_f32 v2, v2, v179
	global_store_short v[0:1], v2, off offset:3008
	v_mul_f32_e32 v0, v12, v84
	v_cvt_pk_bf16_f32 v2, v0, v179
	v_add_co_u32_e32 v0, vcc, s6, v64
	s_mov_b32 s6, 0xc4f4000
	s_nop 0
	v_addc_co_u32_e32 v1, vcc, 0, v65, vcc
	global_store_short v[0:1], v2, off offset:2816
	v_mul_f32_e32 v2, v60, v84
	v_cvt_pk_bf16_f32 v2, v2, v179
	global_store_short v[0:1], v2, off offset:2880
	v_mul_f32_e32 v2, v44, v84
	v_cvt_pk_bf16_f32 v2, v2, v179
	global_store_short v[0:1], v2, off offset:2944
	v_mul_f32_e32 v2, v28, v84
	v_cvt_pk_bf16_f32 v2, v2, v179
	global_store_short v[0:1], v2, off offset:3008
	v_mul_f32_e32 v0, v13, v85
	v_cvt_pk_bf16_f32 v2, v0, v179
	v_add_co_u32_e32 v0, vcc, s6, v64
	v_rcp_f32_e32 v70, v70
	s_nop 0
	v_addc_co_u32_e32 v1, vcc, 0, v65, vcc
	global_store_short v[0:1], v2, off offset:2816
	v_mul_f32_e32 v2, v61, v85
	v_cvt_pk_bf16_f32 v2, v2, v179
	global_store_short v[0:1], v2, off offset:2880
	v_mul_f32_e32 v2, v45, v85
	v_cvt_pk_bf16_f32 v2, v2, v179
	global_store_short v[0:1], v2, off offset:2944
	v_mul_f32_e32 v2, v29, v85
	v_cvt_pk_bf16_f32 v2, v2, v179
	global_store_short v[0:1], v2, off offset:3008
	v_mul_f32_e32 v0, v14, v70
	s_mov_b32 s6, 0xc4f5000
	v_cvt_pk_bf16_f32 v2, v0, v179
	v_add_co_u32_e32 v0, vcc, s6, v64
	v_rcp_f32_e32 v71, v71
	s_nop 0
	v_addc_co_u32_e32 v1, vcc, 0, v65, vcc
	global_store_short v[0:1], v2, off offset:2816
	v_mul_f32_e32 v2, v62, v70
	v_cvt_pk_bf16_f32 v2, v2, v179
	global_store_short v[0:1], v2, off offset:2880
	v_mul_f32_e32 v2, v46, v70
	v_cvt_pk_bf16_f32 v2, v2, v179
	global_store_short v[0:1], v2, off offset:2944
	v_mul_f32_e32 v2, v30, v70
	v_cvt_pk_bf16_f32 v2, v2, v179
	global_store_short v[0:1], v2, off offset:3008
	v_mul_f32_e32 v0, v15, v71
	s_mov_b32 s6, 0xc4f6000
	v_cvt_pk_bf16_f32 v2, v0, v179
	v_add_co_u32_e32 v0, vcc, s6, v64
	s_mov_b64 s[6:7], 0
	s_nop 0
	v_addc_co_u32_e32 v1, vcc, 0, v65, vcc
	global_store_short v[0:1], v2, off offset:2816
	v_mul_f32_e32 v2, v63, v71
	v_cvt_pk_bf16_f32 v2, v2, v179
	global_store_short v[0:1], v2, off offset:2880
	v_mul_f32_e32 v2, v47, v71
	v_cvt_pk_bf16_f32 v2, v2, v179
	global_store_short v[0:1], v2, off offset:2944
	v_mul_f32_e32 v2, v31, v71
	v_cvt_pk_bf16_f32 v2, v2, v179
	global_store_short v[0:1], v2, off offset:3008
	s_waitcnt lgkmcnt(0)
	s_barrier

.LBB0_957:
	v_mbcnt_lo_u32_b32 v52, -1, 0
	v_mbcnt_hi_u32_b32 v52, -1, v52
	s_movk_i32 s18, 0xffe0
	v_or_b32_e32 v20, s34, v52
	v_ashrrev_i32_e32 v16, 4, v20
	v_lshlrev_b32_e32 v22, 3, v52
	v_add_u32_e32 v18, 32, v16
	v_and_b32_e32 v0, 0x78, v22
	v_ashrrev_i32_e32 v17, 31, v16
	v_ashrrev_i32_e32 v19, 31, v18
	v_lshlrev_b32_e32 v23, 1, v0
	v_lshlrev_b64 v[48:49], 9, v[16:17]
	v_lshlrev_b64 v[8:9], 9, v[18:19]
	v_or_b32_e32 v50, v48, v23
	v_mov_b32_e32 v51, v49
	v_or_b32_e32 v8, v8, v23
	v_lshl_add_u64 v[0:1], s[16:17], 0, v[50:51]
	v_lshl_add_u64 v[4:5], s[16:17], 0, v[8:9]
	v_lshl_add_u64 v[10:11], s[8:9], 0, v[50:51]
	v_lshl_add_u64 v[12:13], s[8:9], 0, v[8:9]
	v_ashrrev_i32_e32 v53, 1, v20
	global_load_dwordx4 v[0:3], v[0:1], off
	s_nop 0
	global_load_dwordx4 v[4:7], v[4:5], off
	s_nop 0
	global_load_dwordx4 v[8:11], v[10:11], off
	s_nop 0
	global_load_dwordx4 v[12:15], v[12:13], off
	v_bfi_b32 v20, s18, v53, v52
	v_ashrrev_i32_e32 v21, 31, v20
	v_bfe_u32 v190, v52, 5, 1
	v_lshlrev_b64 v[20:21], 11, v[20:21]
	v_lshl_add_u64 v[20:21], s[6:7], 0, v[20:21]
	v_lshlrev_b32_e32 v176, 4, v190
	v_mov_b32_e32 v177, v179
	v_lshl_add_u64 v[20:21], v[20:21], 0, v[176:177]
	global_load_dwordx4 v[112:115], v[20:21], off
	global_load_dwordx4 v[108:111], v[20:21], off offset:32
	global_load_dwordx4 v[120:123], v[20:21], off offset:64
	global_load_dwordx4 v[124:127], v[20:21], off offset:96
	global_load_dwordx4 v[116:119], v[20:21], off offset:128
	global_load_dwordx4 v[104:107], v[20:21], off offset:160
	global_load_dwordx4 v[100:103], v[20:21], off offset:192
	global_load_dwordx4 v[96:99], v[20:21], off offset:224
	v_mov_b32_e32 v54, s34
	s_movk_i32 s6, 0x70
	v_bfe_u32 v19, v22, 5, 2
	v_and_b32_e32 v22, 0xfffff0, v16
	v_lshlrev_b32_e32 v24, 1, v16
	v_lshrrev_b32_e32 v25, 1, v16
	v_and_b32_e32 v26, 3, v16
	v_bitop3_b32 v17, v52, s6, v54 bitop3:0xc8
	v_lshlrev_b32_e32 v16, 8, v16
	v_and_or_b32 v22, v24, 8, v22
	v_and_or_b32 v24, v25, 4, v26
	v_and_b32_e32 v26, 0xfffff0, v18
	v_lshlrev_b32_e32 v28, 1, v18
	v_bitop3_b32 v16, v23, v16, v17 bitop3:0xde
	v_lshlrev_b32_e32 v18, 8, v18
	v_lshrrev_b32_e32 v22, 1, v22
	v_and_or_b32 v26, v28, 8, v26
	v_and_b32_e32 v177, 31, v52
	v_lshlrev_b32_e32 v55, 4, v52
	v_add_u32_e32 v196, 0, v16
	v_bitop3_b32 v16, v18, v23, v17 bitop3:0xf6
	v_or_b32_e32 v17, v22, v19
	v_lshrrev_b32_e32 v18, 1, v26
	v_lshlrev_b32_e32 v70, 8, v177
	v_and_b32_e32 v71, 0x70, v55
	v_and_b32_e32 v25, 48, v23
	v_lshlrev_b32_e32 v24, 6, v24
	v_add_u32_e32 v197, 0, v16
	v_lshlrev_b32_e32 v16, 9, v17
	v_or_b32_e32 v17, v18, v19
	v_bitop3_b32 v27, v176, v70, v71 bitop3:0xde
	v_or3_b32 v16, v16, v24, v25
	v_lshlrev_b32_e32 v17, 9, v17
	v_add_u32_e32 v195, 0, v27
	v_or3_b32 v17, v17, v24, v25
	v_add_u32_e32 v198, 0, v16
	s_waitcnt vmcnt(0)
	v_add_u32_e32 v199, 0, v17
	s_mov_b32 s7, 0x3fffffc0
	s_add_i32 s6, 0, 0x10000
	v_and_b32_e32 v73, 0xc0, v55
	v_and_b32_e32 v76, 63, v52
	v_lshlrev_b32_e32 v72, 3, v76
	v_and_b32_e32 v180, 0xffffffe0, v53
	s_cmp_lg_u32 0, -1
	s_cselect_b32 s18, 0, 0
	v_readlane_b32 s68, v254, 40
	v_readlane_b32 s69, v254, 41
	v_readlane_b32 s70, v254, 42
	v_readlane_b32 s71, v254, 43
	v_readlane_b32 s72, v254, 44
	v_readlane_b32 s73, v254, 45
	v_readlane_b32 s74, v254, 46
	v_readlane_b32 s75, v254, 47
	s_waitcnt vmcnt(0) lgkmcnt(0)
	ds_write_b128 v198, v[0:3]
	ds_write_b128 v199, v[4:7]
	ds_write_b128 v196, v[8:11] offset:32768
	ds_write_b128 v197, v[12:15] offset:32768
	s_waitcnt lgkmcnt(0)
	s_barrier
	ds_read_b128 v[0:3], v195 offset:32768
	ds_read_b128 v[4:7], v195 offset:40960
	s_waitcnt lgkmcnt(1)
	v_mfma_f32_32x32x16_bf16 v[16:31], v[0:3], v[112:115], 0
	v_or_b32_e32 v0, 32, v176
	v_bitop3_b32 v0, v0, v70, v71 bitop3:0xde
	v_add_u32_e32 v226, 0, v0
	v_readlane_b32 s76, v254, 48
	v_readlane_b32 s77, v254, 49
	v_readlane_b32 s78, v254, 50
	v_readlane_b32 s79, v254, 51
	s_waitcnt lgkmcnt(0)
	v_mfma_f32_32x32x16_bf16 v[32:47], v[4:7], v[112:115], 0
	ds_read_b128 v[0:3], v226 offset:32768
	ds_read_b128 v[4:7], v226 offset:40960
	v_readlane_b32 s80, v254, 52
	v_readlane_b32 s81, v254, 53
	v_readlane_b32 s82, v254, 54
	v_readlane_b32 s83, v254, 55
	s_mov_b32 s68, s69
	s_mov_b32 s70, s69
	s_waitcnt lgkmcnt(1)
	v_mfma_f32_32x32x16_bf16 v[16:31], v[0:3], v[108:111], v[16:31]
	v_or_b32_e32 v0, 64, v176
	v_bitop3_b32 v0, v0, v70, v71 bitop3:0xde
	v_add_u32_e32 v225, 0, v0
	s_mov_b32 s71, s69
	s_mov_b32 s57, s69
	s_mov_b32 s72, s69
	s_mov_b32 s73, s69
	s_waitcnt lgkmcnt(0)
	v_mfma_f32_32x32x16_bf16 v[32:47], v[4:7], v[108:111], v[32:47]
	ds_read_b128 v[0:3], v225 offset:32768
	ds_read_b128 v[4:7], v225 offset:40960
	s_mov_b32 s74, s69
	s_mov_b32 s75, s69
	s_mov_b32 s76, s69
	s_mov_b32 s77, s69
	s_mov_b32 s78, s69
	s_mov_b32 s79, s69
	s_waitcnt lgkmcnt(1)
	v_mfma_f32_32x32x16_bf16 v[16:31], v[0:3], v[120:123], v[16:31]
	v_or_b32_e32 v0, 0x60, v176
	v_bitop3_b32 v0, v0, v70, v71 bitop3:0xde
	v_add_u32_e32 v224, 0, v0
	s_mov_b32 s80, s69
	s_mov_b32 s81, s69
	s_mov_b32 s82, s69
	s_mov_b32 s83, s69
	s_waitcnt lgkmcnt(0)
	v_mfma_f32_32x32x16_bf16 v[32:47], v[4:7], v[120:123], v[32:47]
	ds_read_b128 v[0:3], v224 offset:32768
	ds_read_b128 v[4:7], v224 offset:40960
	v_writelane_b32 v254, s56, 40
	v_lshl_add_u64 v[182:183], s[8:9], 0, v[48:49]
	v_lshl_add_u64 v[184:185], s[16:17], 0, v[48:49]
	v_writelane_b32 v254, s57, 41
	v_writelane_b32 v254, s58, 42
	v_writelane_b32 v254, s59, 43
	s_waitcnt lgkmcnt(1)
	v_mfma_f32_32x32x16_bf16 v[16:31], v[0:3], v[124:127], v[16:31]
	v_or_b32_e32 v0, 0x80, v176
	v_bitop3_b32 v0, v0, v70, v71 bitop3:0xde
	v_add_u32_e32 v223, 0, v0
	ds_read_b128 v[0:3], v223 offset:32768
	v_writelane_b32 v254, s60, 44
	v_writelane_b32 v254, s61, 45
	v_writelane_b32 v254, s62, 46
	s_waitcnt lgkmcnt(1)
	v_mfma_f32_32x32x16_bf16 v[32:47], v[4:7], v[124:127], v[32:47]
	v_bitop3_b32 v4, v52, s7, v54 bitop3:0xc8
	v_lshl_add_u32 v181, v4, 2, s6
	ds_read_b128 v[4:7], v223 offset:40960
	s_mov_b64 s[6:7], 0x8000
	v_lshl_add_u64 v[8:9], v[50:51], 0, s[6:7]
	s_mov_b64 s[6:7], 0xc000
	v_lshl_add_u64 v[10:11], v[50:51], 0, s[6:7]
	s_waitcnt lgkmcnt(1)
	v_mfma_f32_32x32x16_bf16 v[16:31], v[0:3], v[116:119], v[16:31]
	v_or_b32_e32 v0, 0xa0, v176
	v_bitop3_b32 v0, v0, v70, v71 bitop3:0xde
	v_add_u32_e32 v227, 0, v0
	ds_read_b128 v[0:3], v227 offset:32768
	v_lshl_add_u64 v[12:13], s[16:17], 0, v[8:9]
	v_lshl_add_u64 v[8:9], s[8:9], 0, v[8:9]
	v_lshl_add_u64 v[14:15], s[16:17], 0, v[10:11]
	s_waitcnt lgkmcnt(1)
	v_mfma_f32_32x32x16_bf16 v[32:47], v[4:7], v[116:119], v[32:47]
	ds_read_b128 v[4:7], v227 offset:40960
	v_lshl_add_u64 v[10:11], s[8:9], 0, v[10:11]
	global_load_dwordx4 v[54:57], v[12:13], off
	global_load_dwordx4 v[58:61], v[14:15], off
	global_load_dwordx4 v[62:65], v[8:9], off
	global_load_dwordx4 v[66:69], v[10:11], off
	v_lshlrev_b32_e32 v9, 1, v52
	v_and_or_b32 v8, v72, 24, v73
	s_mov_b64 s[6:7], 0x10000
	s_waitcnt lgkmcnt(0)
	v_mfma_f32_32x32x16_bf16 v[16:31], v[0:3], v[104:107], v[16:31]
	v_or_b32_e32 v0, 0xc0, v176
	v_bitop3_b32 v0, v0, v70, v71 bitop3:0xde
	v_add_u32_e32 v228, 0, v0
	ds_read_b128 v[0:3], v228 offset:32768
	v_writelane_b32 v254, s63, 47
	v_writelane_b32 v254, s64, 48
	v_writelane_b32 v254, s65, 49
	v_mfma_f32_32x32x16_bf16 v[32:47], v[4:7], v[104:107], v[32:47]
	v_and_b32_e32 v4, 32, v9
	v_and_b32_e32 v5, 0x100, v72
	v_or3_b32 v53, v8, v4, v5
	ds_read_b128 v[4:7], v228 offset:40960
	v_writelane_b32 v254, s66, 50
	v_writelane_b32 v254, s67, 51
	v_writelane_b32 v254, s68, 52
	s_waitcnt lgkmcnt(0)
	v_mfma_f32_32x32x16_bf16 v[16:31], v[0:3], v[100:103], v[16:31]
	v_or_b32_e32 v0, 0xe0, v176
	v_bitop3_b32 v0, v0, v70, v71 bitop3:0xde
	v_add_u32_e32 v229, 0, v0
	ds_read_b128 v[0:3], v229 offset:32768
	ds_read_b128 v[70:73], v229 offset:40960
	v_add_u32_e32 v194, s18, v53
	v_writelane_b32 v254, s69, 53
	v_mfma_f32_32x32x16_bf16 v[32:47], v[4:7], v[100:103], v[32:47]
	v_writelane_b32 v254, s70, 54
	v_writelane_b32 v254, s71, 55
	v_lshl_add_u32 v191, v177, 2, v181
	v_mov_b32_e32 v192, 0
	s_waitcnt lgkmcnt(0)
	v_mfma_f32_32x32x16_bf16 v[16:31], v[0:3], v[96:99], v[16:31]
	v_mov_b64_e32 v[0:1], s[68:69]
	v_mov_b64_e32 v[14:15], s[82:83]
	v_mov_b64_e32 v[2:3], s[70:71]
	v_mov_b64_e32 v[4:5], s[72:73]
	v_mov_b64_e32 v[6:7], s[74:75]
	v_mov_b64_e32 v[8:9], s[76:77]
	v_mov_b64_e32 v[10:11], s[78:79]
	v_mfma_f32_32x32x16_bf16 v[32:47], v[70:73], v[96:99], v[32:47]
	s_nop 3
	v_max_f32_e32 v70, v17, v17
	v_max_f32_e32 v71, v16, v16
	v_max_f32_e32 v70, v71, v70
	v_max3_f32 v70, v70, v18, v19
	v_max3_f32 v70, v70, v20, v21
	v_max3_f32 v70, v70, v22, v23
	v_max3_f32 v70, v70, v24, v25
	v_max3_f32 v70, v70, v26, v27
	v_max3_f32 v70, v70, v28, v29
	v_max3_f32 v70, v70, v30, v31
	v_max3_f32 v70, v70, v32, v33
	v_max3_f32 v70, v70, v34, v35
	v_max3_f32 v70, v70, v36, v37
	v_max3_f32 v70, v70, v38, v39
	v_max3_f32 v70, v70, v40, v41
	v_max3_f32 v77, v70, v42, v43
	v_lshl_add_u64 v[70:71], v[50:51], 0, s[6:7]
	s_mov_b64 s[6:7], 0x14000
	v_lshl_add_u64 v[72:73], s[16:17], 0, v[70:71]
	v_lshl_add_u64 v[50:51], v[50:51], 0, s[6:7]
	v_lshl_add_u64 v[70:71], s[8:9], 0, v[70:71]
	v_lshl_add_u64 v[74:75], s[16:17], 0, v[50:51]
	global_load_dwordx4 v[128:131], v[72:73], off
	global_load_dwordx4 v[132:135], v[74:75], off
	v_lshl_add_u64 v[50:51], s[8:9], 0, v[50:51]
	global_load_dwordx4 v[136:139], v[70:71], off
	global_load_dwordx4 v[140:143], v[50:51], off
	v_max3_f32 v50, v77, v44, v45
	v_max3_f32 v50, v50, v46, v47
	v_mov_b32_e32 v51, v50
	s_nop 1
	v_permlane32_swap_b32_e32 v50, v51
	v_max_f32_e32 v51, v51, v51
	v_max_f32_e32 v50, v50, v50
	v_max_f32_e32 v50, v50, v51
	v_add_f32_e32 v51, 0x7149f2ca, v50
	s_mov_b32 s6, 0x42b504f3
	v_max_f32_e32 v50, 0xf149f2ca, v50
	v_cmp_ge_f32_e32 vcc, s6, v51
	v_sub_f32_e32 v51, 0xf149f2ca, v50
	v_mul_f32_e32 v51, 0x3e0293ee, v51
	v_exp_f32_e32 v51, v51
	s_cmp_eq_u64 vcc, exec
	s_cselect_b64 vcc, -1, 0
	s_mov_b32 s6, 0x3e0293ee
	v_cndmask_b32_e64 v230, v51, 1.0, vcc
	v_mov_b32_e32 v51, 0xf149f2ca
	v_cndmask_b32_e32 v168, v50, v51, vcc
	v_mul_f32_e32 v50, 0xbe0293ee, v168
	v_fmamk_f32 v16, v16, 0x3e0293ee, v50
	v_exp_f32_e32 v161, v16
	v_fmamk_f32 v16, v17, 0x3e0293ee, v50
	v_exp_f32_e32 v175, v16
	v_fmamk_f32 v16, v18, 0x3e0293ee, v50
	v_exp_f32_e32 v162, v16
	v_fmamk_f32 v16, v19, 0x3e0293ee, v50
	v_exp_f32_e32 v186, v16
	v_fmamk_f32 v16, v20, 0x3e0293ee, v50
	v_exp_f32_e32 v174, v16
	v_fmamk_f32 v16, v21, 0x3e0293ee, v50
	v_exp_f32_e32 v187, v16
	v_fmamk_f32 v16, v22, 0x3e0293ee, v50
	v_exp_f32_e32 v163, v16
	v_fmamk_f32 v16, v23, 0x3e0293ee, v50
	v_exp_f32_e32 v173, v16
	v_fmamk_f32 v16, v24, 0x3e0293ee, v50
	v_exp_f32_e32 v164, v16
	v_fmamk_f32 v16, v25, 0x3e0293ee, v50
	v_exp_f32_e32 v171, v16
	v_fmamk_f32 v16, v26, 0x3e0293ee, v50
	v_exp_f32_e32 v165, v16
	v_fmamk_f32 v16, v27, 0x3e0293ee, v50
	v_exp_f32_e32 v172, v16
	v_fmamk_f32 v16, v28, 0x3e0293ee, v50
	v_exp_f32_e32 v166, v16
	v_fmamk_f32 v16, v29, 0x3e0293ee, v50
	v_pk_fma_f32 v[146:147], v[46:47], s[6:7], v[50:51] op_sel_hi:[1,0,0]
	v_pk_fma_f32 v[150:151], v[44:45], s[6:7], v[50:51] op_sel_hi:[1,0,0]
	v_pk_fma_f32 v[154:155], v[42:43], s[6:7], v[50:51] op_sel_hi:[1,0,0]
	v_pk_fma_f32 v[144:145], v[40:41], s[6:7], v[50:51] op_sel_hi:[1,0,0]
	v_pk_fma_f32 v[148:149], v[38:39], s[6:7], v[50:51] op_sel_hi:[1,0,0]
	v_pk_fma_f32 v[152:153], v[36:37], s[6:7], v[50:51] op_sel_hi:[1,0,0]
	v_pk_fma_f32 v[156:157], v[34:35], s[6:7], v[50:51] op_sel_hi:[1,0,0]
	v_pk_fma_f32 v[158:159], v[32:33], s[6:7], v[50:51] op_sel_hi:[1,0,0]
	v_exp_f32_e32 v169, v16
	v_fmamk_f32 v16, v30, 0x3e0293ee, v50
	v_fmac_f32_e32 v50, 0x3e0293ee, v31
	v_exp_f32_e32 v167, v16
	v_exp_f32_e32 v170, v50
	s_waitcnt vmcnt(4)
	s_addk_i32 s18, 0x4000
	v_and_b32_e32 v16, 15, v52
	v_mov_b64_e32 v[12:13], s[80:81]
	s_waitcnt vmcnt(0)
	ds_write_b128 v198, v[54:57] offset:16384
	ds_write_b128 v199, v[58:61] offset:16384
	ds_write_b128 v196, v[62:65] offset:49152
	ds_write_b128 v197, v[66:69] offset:49152
	v_add_u32_e32 v193, s18, v53
	v_lshlrev_b32_e32 v178, 4, v16
	v_mov_b64_e32 v[62:63], v[14:15]
	v_mov_b64_e32 v[46:47], v[14:15]
	v_mov_b64_e32 v[30:31], v[14:15]
	v_cmp_gt_u32_e64 s[6:7], 32, v76
	v_mov_b64_e32 v[60:61], v[12:13]
	v_mov_b64_e32 v[58:59], v[10:11]
	v_mov_b64_e32 v[56:57], v[8:9]
	v_mov_b64_e32 v[54:55], v[6:7]
	v_mov_b64_e32 v[52:53], v[4:5]
	v_mov_b64_e32 v[50:51], v[2:3]
	v_mov_b64_e32 v[48:49], v[0:1]
	v_mov_b64_e32 v[44:45], v[12:13]
	v_mov_b64_e32 v[42:43], v[10:11]
	v_mov_b64_e32 v[40:41], v[8:9]
	v_mov_b64_e32 v[38:39], v[6:7]
	v_mov_b64_e32 v[36:37], v[4:5]
	v_mov_b64_e32 v[34:35], v[2:3]
	v_mov_b64_e32 v[32:33], v[0:1]
	v_mov_b64_e32 v[28:29], v[12:13]
	v_mov_b64_e32 v[26:27], v[10:11]
	v_mov_b64_e32 v[24:25], v[8:9]
	v_mov_b64_e32 v[22:23], v[6:7]
	v_mov_b64_e32 v[20:21], v[4:5]
	v_mov_b64_e32 v[18:19], v[2:3]
	v_mov_b64_e32 v[16:17], v[0:1]
	s_waitcnt lgkmcnt(0)
	s_barrier
.LBB0_958:
	ds_read_b128 v[64:67], v195 offset:49152
	ds_read_b128 v[68:71], v195 offset:57344
	ds_read_b128 v[232:235], v226 offset:49152
	ds_read_b128 v[236:239], v226 offset:57344
	v_add_f32_e32 v160, 0, v161
	v_add_f32_e32 v160, v175, v160
	s_waitcnt lgkmcnt(3)
	v_mfma_f32_32x32x16_bf16 v[80:95], v[64:67], v[112:115], 0
	v_add_f32_e32 v160, v162, v160
	v_add_f32_e32 v160, v186, v160
	v_add_f32_e32 v160, v174, v160
	v_add_f32_e32 v160, v187, v160
	v_add_f32_e32 v160, v163, v160
	v_add_f32_e32 v160, v173, v160
	v_add_f32_e32 v160, v164, v160
	s_waitcnt lgkmcnt(2)
	v_mfma_f32_32x32x16_bf16 v[64:79], v[68:71], v[112:115], 0
	v_add_f32_e32 v160, v171, v160
	v_add_f32_e32 v160, v165, v160
	v_add_f32_e32 v160, v172, v160
	v_exp_f32_e32 v158, v158
	v_add_f32_e32 v160, v166, v160
	v_exp_f32_e32 v159, v159
	v_add_f32_e32 v160, v169, v160
	s_waitcnt lgkmcnt(1)
	v_mfma_f32_32x32x16_bf16 v[80:95], v[232:235], v[108:111], v[80:95]
	v_exp_f32_e32 v156, v156
	v_add_f32_e32 v160, v167, v160
	v_exp_f32_e32 v157, v157
	v_add_f32_e32 v160, v170, v160
	v_exp_f32_e32 v152, v152
	v_add_f32_e32 v160, v158, v160
	v_exp_f32_e32 v153, v153
	s_waitcnt lgkmcnt(0)
	v_mfma_f32_32x32x16_bf16 v[64:79], v[236:239], v[108:111], v[64:79]
	ds_read_b128 v[232:235], v225 offset:49152
	ds_read_b128 v[236:239], v225 offset:57344
	v_add_f32_e32 v160, v159, v160
	v_exp_f32_e32 v148, v148
	v_add_f32_e32 v160, v156, v160
	v_exp_f32_e32 v149, v149
	v_add_f32_e32 v160, v157, v160
	v_exp_f32_e32 v144, v144
	s_waitcnt lgkmcnt(1)
	v_mfma_f32_32x32x16_bf16 v[80:95], v[232:235], v[120:123], v[80:95]
	v_add_f32_e32 v160, v152, v160
	v_exp_f32_e32 v145, v145
	v_add_f32_e32 v160, v153, v160
	v_exp_f32_e32 v154, v154
	v_add_f32_e32 v160, v148, v160
	v_exp_f32_e32 v155, v155
	v_add_f32_e32 v160, v149, v160
	s_waitcnt lgkmcnt(0)
	v_mfma_f32_32x32x16_bf16 v[64:79], v[236:239], v[120:123], v[64:79]
	ds_read_b128 v[232:235], v224 offset:49152
	ds_read_b128 v[236:239], v224 offset:57344
	v_exp_f32_e32 v150, v150
	v_add_f32_e32 v160, v144, v160
	v_exp_f32_e32 v151, v151
	v_add_f32_e32 v160, v145, v160
	v_exp_f32_e32 v146, v146
	v_add_f32_e32 v160, v154, v160
	s_waitcnt lgkmcnt(1)
	v_mfma_f32_32x32x16_bf16 v[80:95], v[232:235], v[124:127], v[80:95]
	v_exp_f32_e32 v147, v147
	v_add_f32_e32 v160, v155, v160
	v_add_f32_e32 v160, v150, v160
	v_add_f32_e32 v160, v151, v160
	v_add_f32_e32 v160, v146, v160
	v_add_f32_e32 v231, v147, v160
	s_waitcnt lgkmcnt(0)
	v_mfma_f32_32x32x16_bf16 v[64:79], v[236:239], v[124:127], v[64:79]
	ds_read_b128 v[232:235], v223 offset:49152
	ds_read_b128 v[236:239], v223 offset:57344
	s_waitcnt lgkmcnt(1)
	v_mfma_f32_32x32x16_bf16 v[80:95], v[232:235], v[116:119], v[80:95]
	s_waitcnt lgkmcnt(0)
	v_mfma_f32_32x32x16_bf16 v[64:79], v[236:239], v[116:119], v[64:79]
	ds_read_b128 v[232:235], v227 offset:49152
	ds_read_b128 v[236:239], v227 offset:57344
	s_waitcnt lgkmcnt(1)
	v_mfma_f32_32x32x16_bf16 v[80:95], v[232:235], v[104:107], v[80:95]
	s_waitcnt lgkmcnt(0)
	v_mfma_f32_32x32x16_bf16 v[64:79], v[236:239], v[104:107], v[64:79]
	ds_read_b128 v[232:235], v228 offset:49152
	ds_read_b128 v[236:239], v228 offset:57344
	s_waitcnt lgkmcnt(1)
	v_mfma_f32_32x32x16_bf16 v[80:95], v[232:235], v[100:103], v[80:95]
	s_waitcnt lgkmcnt(0)
	v_mfma_f32_32x32x16_bf16 v[64:79], v[236:239], v[100:103], v[64:79]
	ds_read_b128 v[232:235], v229 offset:49152
	ds_read_b128 v[236:239], v229 offset:57344
	v_cvt_pk_bf16_f32 v160, v161, v175
	v_cvt_pk_bf16_f32 v161, v162, v186
	v_cvt_pk_bf16_f32 v162, v174, v187
	v_cvt_pk_bf16_f32 v163, v163, v173
	v_cvt_pk_bf16_f32 v164, v164, v171
	v_cvt_pk_bf16_f32 v165, v165, v172
	s_waitcnt lgkmcnt(1)
	v_mfma_f32_32x32x16_bf16 v[80:95], v[232:235], v[96:99], v[80:95]
	v_mov_b32_e32 v232, v231
	s_nop 1
	v_permlane32_swap_b32_e32 v231, v232
	v_permlane32_swap_b32_e32 v160, v162
	v_cvt_pk_bf16_f32 v166, v166, v169
	v_cvt_pk_bf16_f32 v167, v167, v170
	s_waitcnt lgkmcnt(0)
	v_mfma_f32_32x32x16_bf16 v[64:79], v[236:239], v[96:99], v[64:79]
	v_cvt_pk_bf16_f32 v170, v158, v159
	v_cvt_pk_bf16_f32 v171, v156, v157
	v_cvt_pk_bf16_f32 v172, v152, v153
	v_cvt_pk_bf16_f32 v173, v148, v149
	v_cvt_pk_bf16_f32 v234, v144, v145
	v_cvt_pk_bf16_f32 v235, v154, v155
	v_cvt_pk_bf16_f32 v236, v150, v151
	v_cvt_pk_bf16_f32 v237, v146, v147
	v_permlane32_swap_b32_e32 v161, v163
	v_permlane32_swap_b32_e32 v164, v166
	v_permlane32_swap_b32_e32 v165, v167
	v_permlane32_swap_b32_e32 v170, v172
	v_permlane32_swap_b32_e32 v171, v173
	v_permlane32_swap_b32_e32 v234, v236
	v_permlane32_swap_b32_e32 v235, v237
	v_lshl_add_u64 v[188:189], v[184:185], 0, v[178:179]
	s_mov_b32 s8, 0x18000
	v_add_co_u32_e32 v144, vcc, s8, v188
	s_mov_b32 s9, 0x1c000
	s_nop 0
	v_addc_co_u32_e32 v145, vcc, 0, v189, vcc
	v_add_co_u32_e32 v148, vcc, s9, v188
	v_lshl_add_u64 v[186:187], v[182:183], 0, v[178:179]
	s_nop 0
	v_addc_co_u32_e32 v149, vcc, 0, v189, vcc
	v_add_co_u32_e32 v152, vcc, s8, v186
	global_load_dwordx4 v[144:147], v[144:145], off
	s_nop 0
	global_load_dwordx4 v[148:151], v[148:149], off
	v_addc_co_u32_e32 v153, vcc, 0, v187, vcc
	v_add_co_u32_e32 v156, vcc, s9, v186
	s_nop 1
	v_addc_co_u32_e32 v157, vcc, 0, v187, vcc
	global_load_dwordx4 v[152:155], v[152:153], off
	s_nop 0
	global_load_dwordx4 v[156:159], v[156:157], off
	ds_read_b64_tr_b16 v[238:239], v194 offset:0
	ds_read_b64_tr_b16 v[240:241], v194 offset:0x800
	ds_read_b64_tr_b16 v[242:243], v194 offset:0x1000
	ds_read_b64_tr_b16 v[244:245], v194 offset:0x1800
	ds_read_b64_tr_b16 v[246:247], v194 offset:0x2000
	ds_read_b64_tr_b16 v[248:249], v194 offset:0x2800
	ds_read_b64_tr_b16 v[212:213], v194 offset:0x3000
	ds_read_b64_tr_b16 v[214:215], v194 offset:0x3800
	s_waitcnt lgkmcnt(0)
	s_nop 0
	v_mfma_f32_32x32x16_bf16 v[0:15], v[160:163], v[238:241], v[0:15]
	v_mfma_f32_32x32x16_bf16 v[0:15], v[164:167], v[242:245], v[0:15]
	v_mfma_f32_32x32x16_bf16 v[0:15], v[170:173], v[246:249], v[0:15]
	v_mfma_f32_32x32x16_bf16 v[0:15], v[234:237], v[212:215], v[0:15]
	ds_read_b64_tr_b16 v[212:213], v194 offset:0x200
	ds_read_b64_tr_b16 v[214:215], v194 offset:0xa00
	ds_read_b64_tr_b16 v[238:239], v194 offset:0x1200
	ds_read_b64_tr_b16 v[240:241], v194 offset:0x1a00
	ds_read_b64_tr_b16 v[242:243], v194 offset:0x2200
	ds_read_b64_tr_b16 v[244:245], v194 offset:0x2a00
	ds_read_b64_tr_b16 v[246:247], v194 offset:0x3200
	ds_read_b64_tr_b16 v[248:249], v194 offset:0x3a00
	s_waitcnt lgkmcnt(0)
	s_nop 0
	v_mfma_f32_32x32x16_bf16 v[48:63], v[160:163], v[212:215], v[48:63]
	ds_read_b64_tr_b16 v[212:213], v194 offset:0x400
	ds_read_b64_tr_b16 v[214:215], v194 offset:0xc00
	v_mfma_f32_32x32x16_bf16 v[48:63], v[164:167], v[238:241], v[48:63]
	ds_read_b64_tr_b16 v[238:239], v194 offset:0x1400
	ds_read_b64_tr_b16 v[240:241], v194 offset:0x1c00
	v_mfma_f32_32x32x16_bf16 v[48:63], v[170:173], v[242:245], v[48:63]
	ds_read_b64_tr_b16 v[242:243], v194 offset:0x2400
	ds_read_b64_tr_b16 v[244:245], v194 offset:0x2c00
	v_mfma_f32_32x32x16_bf16 v[48:63], v[234:237], v[246:249], v[48:63]
	ds_read_b64_tr_b16 v[246:247], v194 offset:0x3400
	ds_read_b64_tr_b16 v[248:249], v194 offset:0x3c00
	s_waitcnt lgkmcnt(0)
	v_mfma_f32_32x32x16_bf16 v[32:47], v[160:163], v[212:215], v[32:47]
	ds_read_b64_tr_b16 v[212:213], v194 offset:0x600
	ds_read_b64_tr_b16 v[214:215], v194 offset:0xe00
	v_mfma_f32_32x32x16_bf16 v[32:47], v[164:167], v[238:241], v[32:47]
	ds_read_b64_tr_b16 v[238:239], v194 offset:0x1600
	ds_read_b64_tr_b16 v[240:241], v194 offset:0x1e00
	v_mfma_f32_32x32x16_bf16 v[32:47], v[170:173], v[242:245], v[32:47]
	ds_read_b64_tr_b16 v[242:243], v194 offset:0x2600
	ds_read_b64_tr_b16 v[244:245], v194 offset:0x2e00
	v_mfma_f32_32x32x16_bf16 v[32:47], v[234:237], v[246:249], v[32:47]
	ds_read_b64_tr_b16 v[246:247], v194 offset:0x3600
	ds_read_b64_tr_b16 v[248:249], v194 offset:0x3e00
	s_waitcnt lgkmcnt(0)
	v_mfma_f32_32x32x16_bf16 v[16:31], v[160:163], v[212:215], v[16:31]
	v_max_f32_e32 v160, v81, v81
	v_max_f32_e32 v161, v80, v80
	v_max_f32_e32 v160, v161, v160
	v_max3_f32 v160, v160, v82, v83
	v_max3_f32 v160, v160, v84, v85
	v_max3_f32 v160, v160, v86, v87
	v_max3_f32 v160, v160, v88, v89
	v_max3_f32 v160, v160, v90, v91
	v_max3_f32 v160, v160, v92, v93
	v_mfma_f32_32x32x16_bf16 v[16:31], v[164:167], v[238:241], v[16:31]
	v_max3_f32 v160, v160, v94, v95
	v_max3_f32 v160, v160, v64, v65
	v_max3_f32 v160, v160, v66, v67
	v_max3_f32 v160, v160, v68, v69
	v_max3_f32 v160, v160, v70, v71
	v_max3_f32 v160, v160, v72, v73
	v_max3_f32 v160, v160, v74, v75
	v_max3_f32 v160, v160, v76, v77
	v_mfma_f32_32x32x16_bf16 v[16:31], v[170:173], v[242:245], v[16:31]
	v_max3_f32 v160, v160, v78, v79
	v_mov_b32_e32 v161, v160
	s_nop 1
	v_permlane32_swap_b32_e32 v160, v161
	v_max_f32_e32 v161, v161, v161
	v_max_f32_e32 v160, v160, v160
	v_max_f32_e32 v160, v160, v161
	v_sub_f32_e32 v161, v160, v168
	s_mov_b32 s8, 0x42b504f3
	v_cmp_ge_f32_e32 vcc, s8, v161
	v_max_f32_e32 v161, v168, v168
	v_max_f32_e32 v160, v161, v160
	v_mfma_f32_32x32x16_bf16 v[16:31], v[234:237], v[246:249], v[16:31]
	v_sub_f32_e32 v161, v168, v160
	v_mul_f32_e32 v161, 0x3e0293ee, v161
	v_exp_f32_e32 v161, v161
	s_cmp_eq_u64 vcc, exec
	s_cselect_b64 s[8:9], -1, 0
	s_waitcnt lgkmcnt(0)
	s_barrier
	s_waitcnt vmcnt(4)
	v_cndmask_b32_e64 v233, v161, 1.0, s[8:9]
	v_cmp_gt_f32_e32 vcc, 1.0, v233
	ds_write_b128 v198, v[128:131]
	ds_write_b128 v199, v[132:135]
	ds_write_b128 v196, v[136:139] offset:32768
	ds_write_b128 v197, v[140:143] offset:32768
	s_cbranch_vccz .LBB0_962
	s_and_saveexec_b64 s[16:17], s[6:7]
	ds_write_b32 v191, v233 offset:128
	s_or_b64 exec, exec, s[16:17]
	s_waitcnt lgkmcnt(0)
	v_add_u32_e32 v161, v181, v176
	ds_read_b128 v[162:165], v161 offset:224
	ds_read_b128 v[170:173], v161 offset:192
	ds_read_b128 v[212:215], v161 offset:160
	ds_read_b128 v[234:237], v161 offset:128
	s_waitcnt lgkmcnt(0)
	v_pk_mul_f32 v[12:13], v[12:13], v[162:163]
	v_pk_mul_f32 v[8:9], v[8:9], v[170:171]
	v_pk_mul_f32 v[4:5], v[4:5], v[212:213]
	v_pk_mul_f32 v[14:15], v[14:15], v[164:165]
	v_pk_mul_f32 v[10:11], v[10:11], v[172:173]
	v_pk_mul_f32 v[6:7], v[6:7], v[214:215]
	v_pk_mul_f32 v[2:3], v[2:3], v[236:237]
	v_pk_mul_f32 v[0:1], v[0:1], v[234:235]
	v_pk_mul_f32 v[60:61], v[60:61], v[162:163]
	v_pk_mul_f32 v[56:57], v[56:57], v[170:171]
	v_pk_mul_f32 v[52:53], v[52:53], v[212:213]
	v_pk_mul_f32 v[62:63], v[62:63], v[164:165]
	v_pk_mul_f32 v[58:59], v[58:59], v[172:173]
	v_pk_mul_f32 v[54:55], v[54:55], v[214:215]
	v_pk_mul_f32 v[50:51], v[50:51], v[236:237]
	v_pk_mul_f32 v[48:49], v[48:49], v[234:235]
	v_pk_mul_f32 v[44:45], v[44:45], v[162:163]
	v_pk_mul_f32 v[40:41], v[40:41], v[170:171]
	v_pk_mul_f32 v[36:37], v[36:37], v[212:213]
	v_pk_mul_f32 v[46:47], v[46:47], v[164:165]
	v_pk_mul_f32 v[42:43], v[42:43], v[172:173]
	v_pk_mul_f32 v[38:39], v[38:39], v[214:215]
	v_pk_mul_f32 v[34:35], v[34:35], v[236:237]
	v_pk_mul_f32 v[32:33], v[32:33], v[234:235]
	v_pk_mul_f32 v[28:29], v[28:29], v[162:163]
	v_pk_mul_f32 v[24:25], v[24:25], v[170:171]
	v_pk_mul_f32 v[20:21], v[20:21], v[212:213]
	v_pk_mul_f32 v[30:31], v[30:31], v[164:165]
	v_pk_mul_f32 v[26:27], v[26:27], v[172:173]
	v_pk_mul_f32 v[22:23], v[22:23], v[214:215]
	v_pk_mul_f32 v[18:19], v[18:19], v[236:237]
	v_pk_mul_f32 v[16:17], v[16:17], v[234:235]
.LBB0_962:
	v_cndmask_b32_e64 v234, v160, v168, s[8:9]
	v_mul_f32_e32 v235, 0xbe0293ee, v234
	v_fmamk_f32 v80, v80, 0x3e0293ee, v235
	v_fmamk_f32 v81, v81, 0x3e0293ee, v235
	v_fmamk_f32 v82, v82, 0x3e0293ee, v235
	v_fmamk_f32 v83, v83, 0x3e0293ee, v235
	v_fmamk_f32 v84, v84, 0x3e0293ee, v235
	v_fmamk_f32 v85, v85, 0x3e0293ee, v235
	v_fmamk_f32 v86, v86, 0x3e0293ee, v235
	v_fmamk_f32 v87, v87, 0x3e0293ee, v235
	v_fmamk_f32 v88, v88, 0x3e0293ee, v235
	v_fmamk_f32 v89, v89, 0x3e0293ee, v235
	v_fmamk_f32 v90, v90, 0x3e0293ee, v235
	v_fmamk_f32 v91, v91, 0x3e0293ee, v235
	v_fmamk_f32 v92, v92, 0x3e0293ee, v235
	v_fmamk_f32 v93, v93, 0x3e0293ee, v235
	v_fmamk_f32 v94, v94, 0x3e0293ee, v235
	v_fmamk_f32 v95, v95, 0x3e0293ee, v235
	v_exp_f32_e32 v160, v80
	v_exp_f32_e32 v175, v81
	v_exp_f32_e32 v161, v82
	v_exp_f32_e32 v174, v83
	v_exp_f32_e32 v162, v84
	v_exp_f32_e32 v173, v85
	v_exp_f32_e32 v163, v86
	v_exp_f32_e32 v172, v87
	v_exp_f32_e32 v164, v88
	v_exp_f32_e32 v171, v89
	v_exp_f32_e32 v165, v90
	v_exp_f32_e32 v170, v91
	v_exp_f32_e32 v166, v92
	v_exp_f32_e32 v169, v93
	v_exp_f32_e32 v167, v94
	v_exp_f32_e32 v168, v95
	v_fmamk_f32 v244, v64, 0x3e0293ee, v235
	v_fmamk_f32 v245, v65, 0x3e0293ee, v235
	v_fmamk_f32 v246, v66, 0x3e0293ee, v235
	v_fmamk_f32 v247, v67, 0x3e0293ee, v235
	v_fmamk_f32 v248, v68, 0x3e0293ee, v235
	v_fmamk_f32 v237, v69, 0x3e0293ee, v235
	v_fmamk_f32 v238, v70, 0x3e0293ee, v235
	v_fmamk_f32 v239, v71, 0x3e0293ee, v235
	v_fmamk_f32 v240, v72, 0x3e0293ee, v235
	v_fmamk_f32 v241, v73, 0x3e0293ee, v235
	v_fmamk_f32 v242, v74, 0x3e0293ee, v235
	v_fmamk_f32 v243, v75, 0x3e0293ee, v235
	v_fmamk_f32 v236, v76, 0x3e0293ee, v235
	v_fmamk_f32 v249, v77, 0x3e0293ee, v235
	v_fmamk_f32 v250, v78, 0x3e0293ee, v235
	v_fmac_f32_e32 v235, 0x3e0293ee, v79
	s_waitcnt lgkmcnt(0)
	s_barrier
	ds_read_b128 v[64:67], v195 offset:32768
	ds_read_b128 v[68:71], v195 offset:40960
	ds_read_b128 v[212:215], v226 offset:32768
	ds_read_b128 v[204:207], v226 offset:40960
	s_waitcnt lgkmcnt(0)
	v_mfma_f32_32x32x16_bf16 v[80:95], v[64:67], v[112:115], 0
	v_mfma_f32_32x32x16_bf16 v[64:79], v[68:71], v[112:115], 0
	v_mfma_f32_32x32x16_bf16 v[80:95], v[212:215], v[108:111], v[80:95]
	v_mfma_f32_32x32x16_bf16 v[64:79], v[204:207], v[108:111], v[64:79]
	ds_read_b128 v[204:207], v225 offset:32768
	ds_read_b128 v[212:215], v225 offset:40960
	s_waitcnt lgkmcnt(0)
	v_mfma_f32_32x32x16_bf16 v[80:95], v[204:207], v[120:123], v[80:95]
	v_mfma_f32_32x32x16_bf16 v[64:79], v[212:215], v[120:123], v[64:79]
	ds_read_b128 v[204:207], v224 offset:32768
	ds_read_b128 v[212:215], v224 offset:40960
	s_waitcnt lgkmcnt(0)
	v_mfma_f32_32x32x16_bf16 v[80:95], v[204:207], v[124:127], v[80:95]
	v_mfma_f32_32x32x16_bf16 v[64:79], v[212:215], v[124:127], v[64:79]
	ds_read_b128 v[204:207], v223 offset:32768
	ds_read_b128 v[212:215], v223 offset:40960
	s_waitcnt lgkmcnt(0)
	v_mfma_f32_32x32x16_bf16 v[80:95], v[204:207], v[116:119], v[80:95]
	v_mfma_f32_32x32x16_bf16 v[64:79], v[212:215], v[116:119], v[64:79]
	ds_read_b128 v[204:207], v227 offset:32768
	ds_read_b128 v[212:215], v227 offset:40960
	s_waitcnt lgkmcnt(0)
	v_mfma_f32_32x32x16_bf16 v[80:95], v[204:207], v[104:107], v[80:95]
	v_mfma_f32_32x32x16_bf16 v[64:79], v[212:215], v[104:107], v[64:79]
	ds_read_b128 v[204:207], v228 offset:32768
	ds_read_b128 v[212:215], v228 offset:40960
	s_waitcnt lgkmcnt(0)
	v_mfma_f32_32x32x16_bf16 v[80:95], v[204:207], v[100:103], v[80:95]
	v_mfma_f32_32x32x16_bf16 v[64:79], v[212:215], v[100:103], v[64:79]
	ds_read_b128 v[204:207], v229 offset:32768
	ds_read_b128 v[212:215], v229 offset:40960
	s_waitcnt lgkmcnt(0)
	v_mfma_f32_32x32x16_bf16 v[80:95], v[204:207], v[96:99], v[80:95]
	v_exp_f32_e32 v204, v244
	v_exp_f32_e32 v244, v235
	v_add_f32_e32 v235, 0, v160
	v_add_f32_e32 v235, v175, v235
	v_add_f32_e32 v235, v161, v235
	v_add_f32_e32 v235, v174, v235
	v_add_f32_e32 v235, v162, v235
	v_add_f32_e32 v235, v173, v235
	v_add_f32_e32 v235, v163, v235
	v_add_f32_e32 v235, v172, v235
	v_add_f32_e32 v235, v164, v235
	v_add_f32_e32 v235, v171, v235
	v_add_f32_e32 v235, v165, v235
	v_add_f32_e32 v235, v170, v235
	v_add_f32_e32 v235, v166, v235
	v_exp_f32_e32 v205, v245
	v_add_f32_e32 v235, v169, v235
	v_exp_f32_e32 v206, v246
	v_add_f32_e32 v235, v167, v235
	v_exp_f32_e32 v207, v247
	v_add_f32_e32 v235, v168, v235
	v_mfma_f32_32x32x16_bf16 v[64:79], v[212:215], v[96:99], v[64:79]
	v_exp_f32_e32 v212, v248
	v_add_f32_e32 v235, v204, v235
	v_exp_f32_e32 v213, v237
	v_add_f32_e32 v235, v205, v235
	v_exp_f32_e32 v214, v238
	v_add_f32_e32 v235, v206, v235
	v_exp_f32_e32 v215, v239
	v_add_f32_e32 v235, v207, v235
	v_exp_f32_e32 v237, v240
	v_add_f32_e32 v235, v212, v235
	v_exp_f32_e32 v238, v241
	v_add_f32_e32 v235, v213, v235
	v_exp_f32_e32 v239, v242
	v_add_f32_e32 v235, v214, v235
	v_exp_f32_e32 v240, v243
	v_add_f32_e32 v235, v215, v235
	v_exp_f32_e32 v241, v236
	v_add_f32_e32 v235, v237, v235
	v_exp_f32_e32 v242, v249
	v_add_f32_e32 v235, v238, v235
	v_exp_f32_e32 v243, v250
	v_add_f32_e32 v235, v239, v235
	v_add_f32_e32 v235, v240, v235
	v_add_f32_e32 v235, v241, v235
	v_add_f32_e32 v235, v242, v235
	v_add_f32_e32 v235, v243, v235
	v_add_f32_e32 v235, v244, v235
	v_mov_b32_e32 v236, v235
	v_cvt_pk_bf16_f32 v160, v160, v175
	v_cvt_pk_bf16_f32 v161, v161, v174
	v_cvt_pk_bf16_f32 v162, v162, v173
	v_cvt_pk_bf16_f32 v163, v163, v172
	v_cvt_pk_bf16_f32 v164, v164, v171
	v_cvt_pk_bf16_f32 v165, v165, v170
	v_cvt_pk_bf16_f32 v166, v166, v169
	v_cvt_pk_bf16_f32 v167, v167, v168
	v_cvt_pk_bf16_f32 v168, v204, v205
	v_cvt_pk_bf16_f32 v169, v206, v207
	v_cvt_pk_bf16_f32 v170, v212, v213
	v_cvt_pk_bf16_f32 v171, v214, v215
	v_cvt_pk_bf16_f32 v172, v237, v238
	v_cvt_pk_bf16_f32 v173, v239, v240
	v_cvt_pk_bf16_f32 v174, v241, v242
	v_cvt_pk_bf16_f32 v175, v243, v244
	s_nop 1
	v_permlane32_swap_b32_e32 v235, v236
	v_permlane32_swap_b32_e32 v160, v162
	v_permlane32_swap_b32_e32 v161, v163
	v_permlane32_swap_b32_e32 v164, v166
	v_permlane32_swap_b32_e32 v165, v167
	v_permlane32_swap_b32_e32 v168, v170
	v_permlane32_swap_b32_e32 v169, v171
	v_permlane32_swap_b32_e32 v172, v174
	v_permlane32_swap_b32_e32 v173, v175
	s_cmp_ge_u32 s30, s31
	s_cselect_b64 s[16:17], -1, 0
	s_and_b64 vcc, exec, s[16:17]
	s_cbranch_vccnz .Lmy_att_skip
	v_add_co_u32_e32 v128, vcc, 0x20000, v188
	s_nop 1
	v_addc_co_u32_e32 v129, vcc, 0, v189, vcc
	v_add_co_u32_e32 v132, vcc, 0x24000, v188
	s_nop 1
	v_addc_co_u32_e32 v133, vcc, 0, v189, vcc
	v_add_co_u32_e32 v136, vcc, 0x20000, v186
	global_load_dwordx4 v[128:131], v[128:129], off
	s_nop 0
	global_load_dwordx4 v[132:135], v[132:133], off
	v_addc_co_u32_e32 v137, vcc, 0, v187, vcc
	v_add_co_u32_e32 v140, vcc, 0x24000, v186
	s_nop 1
	v_addc_co_u32_e32 v141, vcc, 0, v187, vcc
	global_load_dwordx4 v[136:139], v[136:137], off
	s_nop 0
	global_load_dwordx4 v[140:143], v[140:141], off
.LBB0_964:
	ds_read_b64_tr_b16 v[186:187], v193 offset:0
	ds_read_b64_tr_b16 v[188:189], v193 offset:0x800
	ds_read_b64_tr_b16 v[204:205], v193 offset:0x1000
	ds_read_b64_tr_b16 v[206:207], v193 offset:0x1800
	ds_read_b64_tr_b16 v[212:213], v193 offset:0x2000
	ds_read_b64_tr_b16 v[214:215], v193 offset:0x2800
	ds_read_b64_tr_b16 v[238:239], v193 offset:0x3000
	ds_read_b64_tr_b16 v[240:241], v193 offset:0x3800
	s_waitcnt lgkmcnt(0)
	s_nop 0
	v_mfma_f32_32x32x16_bf16 v[0:15], v[160:163], v[186:189], v[0:15]
	ds_read_b64_tr_b16 v[186:187], v193 offset:0x200
	ds_read_b64_tr_b16 v[188:189], v193 offset:0xa00
	v_mfma_f32_32x32x16_bf16 v[0:15], v[164:167], v[204:207], v[0:15]
	ds_read_b64_tr_b16 v[204:205], v193 offset:0x1200
	ds_read_b64_tr_b16 v[206:207], v193 offset:0x1a00
	v_mfma_f32_32x32x16_bf16 v[0:15], v[168:171], v[212:215], v[0:15]
	ds_read_b64_tr_b16 v[212:213], v193 offset:0x2200
	ds_read_b64_tr_b16 v[214:215], v193 offset:0x2a00
	v_mfma_f32_32x32x16_bf16 v[0:15], v[172:175], v[238:241], v[0:15]
	ds_read_b64_tr_b16 v[238:239], v193 offset:0x3200
	ds_read_b64_tr_b16 v[240:241], v193 offset:0x3a00
	s_waitcnt lgkmcnt(0)
	v_mfma_f32_32x32x16_bf16 v[48:63], v[160:163], v[186:189], v[48:63]
	ds_read_b64_tr_b16 v[186:187], v193 offset:0x400
	ds_read_b64_tr_b16 v[188:189], v193 offset:0xc00
	v_mfma_f32_32x32x16_bf16 v[48:63], v[164:167], v[204:207], v[48:63]
	ds_read_b64_tr_b16 v[204:205], v193 offset:0x1400
	ds_read_b64_tr_b16 v[206:207], v193 offset:0x1c00
	v_mfma_f32_32x32x16_bf16 v[48:63], v[168:171], v[212:215], v[48:63]
	ds_read_b64_tr_b16 v[212:213], v193 offset:0x2400
	ds_read_b64_tr_b16 v[214:215], v193 offset:0x2c00
	v_mfma_f32_32x32x16_bf16 v[48:63], v[172:175], v[238:241], v[48:63]
	ds_read_b64_tr_b16 v[238:239], v193 offset:0x3400
	ds_read_b64_tr_b16 v[240:241], v193 offset:0x3c00
	s_waitcnt lgkmcnt(0)
	v_mfma_f32_32x32x16_bf16 v[32:47], v[160:163], v[186:189], v[32:47]
	ds_read_b64_tr_b16 v[186:187], v193 offset:0x600
	ds_read_b64_tr_b16 v[188:189], v193 offset:0xe00
	v_mfma_f32_32x32x16_bf16 v[32:47], v[164:167], v[204:207], v[32:47]
	ds_read_b64_tr_b16 v[204:205], v193 offset:0x1600
	ds_read_b64_tr_b16 v[206:207], v193 offset:0x1e00
	v_mfma_f32_32x32x16_bf16 v[32:47], v[168:171], v[212:215], v[32:47]
	ds_read_b64_tr_b16 v[212:213], v193 offset:0x2600
	ds_read_b64_tr_b16 v[214:215], v193 offset:0x2e00
	v_mfma_f32_32x32x16_bf16 v[32:47], v[172:175], v[238:241], v[32:47]
	ds_read_b64_tr_b16 v[238:239], v193 offset:0x3600
	ds_read_b64_tr_b16 v[240:241], v193 offset:0x3e00
	s_waitcnt lgkmcnt(0)
	v_mfma_f32_32x32x16_bf16 v[16:31], v[160:163], v[186:189], v[16:31]
	v_max_f32_e32 v160, v81, v81
	v_max_f32_e32 v161, v80, v80
	v_max_f32_e32 v160, v161, v160
	v_max3_f32 v160, v160, v82, v83
	v_max3_f32 v160, v160, v84, v85
	v_max3_f32 v160, v160, v86, v87
	v_max3_f32 v160, v160, v88, v89
	v_max3_f32 v160, v160, v90, v91
	v_max3_f32 v160, v160, v92, v93
	v_mfma_f32_32x32x16_bf16 v[16:31], v[164:167], v[204:207], v[16:31]
	v_max3_f32 v160, v160, v94, v95
	v_max3_f32 v160, v160, v64, v65
	v_max3_f32 v160, v160, v66, v67
	v_max3_f32 v160, v160, v68, v69
	v_max3_f32 v160, v160, v70, v71
	v_max3_f32 v160, v160, v72, v73
	v_max3_f32 v160, v160, v74, v75
	v_max3_f32 v160, v160, v76, v77
	v_mfma_f32_32x32x16_bf16 v[16:31], v[168:171], v[212:215], v[16:31]
	v_max3_f32 v160, v160, v78, v79
	v_mov_b32_e32 v161, v160
	s_nop 1
	v_permlane32_swap_b32_e32 v160, v161
	v_max_f32_e32 v161, v161, v161
	v_max_f32_e32 v160, v160, v160
	v_max_f32_e32 v160, v160, v161
	v_sub_f32_e32 v161, v160, v234
	s_mov_b32 s8, 0x42b504f3
	v_cmp_ge_f32_e32 vcc, s8, v161
	v_max_f32_e32 v161, v234, v234
	v_max_f32_e32 v161, v161, v160
	v_mfma_f32_32x32x16_bf16 v[16:31], v[172:175], v[238:241], v[16:31]
	v_sub_f32_e32 v160, v234, v161
	v_mul_f32_e32 v160, 0x3e0293ee, v160
	v_exp_f32_e32 v160, v160
	s_cmp_eq_u64 vcc, exec
	s_cselect_b64 s[8:9], -1, 0
	s_waitcnt lgkmcnt(0)
	s_barrier
	s_waitcnt vmcnt(4)
	v_cndmask_b32_e64 v160, v160, 1.0, s[8:9]
	v_cmp_gt_f32_e32 vcc, 1.0, v160
	ds_write_b128 v198, v[144:147] offset:16384
	ds_write_b128 v199, v[148:151] offset:16384
	ds_write_b128 v196, v[152:155] offset:49152
	ds_write_b128 v197, v[156:159] offset:49152
	s_cbranch_vccz .LBB0_968
	s_and_saveexec_b64 s[18:19], s[6:7]
	ds_write_b32 v191, v160 offset:128
	s_or_b64 exec, exec, s[18:19]
	s_waitcnt lgkmcnt(0)
	v_add_u32_e32 v156, v181, v176
	ds_read_b128 v[144:147], v156 offset:224
	ds_read_b128 v[148:151], v156 offset:192
	ds_read_b128 v[152:155], v156 offset:160
	ds_read_b128 v[156:159], v156 offset:128
	s_waitcnt lgkmcnt(3)
	v_pk_mul_f32 v[12:13], v[12:13], v[144:145]
	s_waitcnt lgkmcnt(2)
	v_pk_mul_f32 v[8:9], v[8:9], v[148:149]
	s_waitcnt lgkmcnt(1)
	v_pk_mul_f32 v[4:5], v[4:5], v[152:153]
	v_pk_mul_f32 v[14:15], v[14:15], v[146:147]
	v_pk_mul_f32 v[10:11], v[10:11], v[150:151]
	v_pk_mul_f32 v[6:7], v[6:7], v[154:155]
	s_waitcnt lgkmcnt(0)
	v_pk_mul_f32 v[2:3], v[2:3], v[158:159]
	v_pk_mul_f32 v[0:1], v[0:1], v[156:157]
	v_pk_mul_f32 v[60:61], v[60:61], v[144:145]
	v_pk_mul_f32 v[56:57], v[56:57], v[148:149]
	v_pk_mul_f32 v[52:53], v[52:53], v[152:153]
	v_pk_mul_f32 v[62:63], v[62:63], v[146:147]
	v_pk_mul_f32 v[58:59], v[58:59], v[150:151]
	v_pk_mul_f32 v[54:55], v[54:55], v[154:155]
	v_pk_mul_f32 v[50:51], v[50:51], v[158:159]
	v_pk_mul_f32 v[48:49], v[48:49], v[156:157]
	v_pk_mul_f32 v[44:45], v[44:45], v[144:145]
	v_pk_mul_f32 v[40:41], v[40:41], v[148:149]
	v_pk_mul_f32 v[36:37], v[36:37], v[152:153]
	v_pk_mul_f32 v[46:47], v[46:47], v[146:147]
	v_pk_mul_f32 v[42:43], v[42:43], v[150:151]
	v_pk_mul_f32 v[38:39], v[38:39], v[154:155]
	v_pk_mul_f32 v[34:35], v[34:35], v[158:159]
	v_pk_mul_f32 v[32:33], v[32:33], v[156:157]
	v_pk_mul_f32 v[28:29], v[28:29], v[144:145]
	v_pk_mul_f32 v[24:25], v[24:25], v[148:149]
	v_pk_mul_f32 v[20:21], v[20:21], v[152:153]
	v_pk_mul_f32 v[30:31], v[30:31], v[146:147]
	v_pk_mul_f32 v[26:27], v[26:27], v[150:151]
	v_pk_mul_f32 v[22:23], v[22:23], v[154:155]
	v_pk_mul_f32 v[18:19], v[18:19], v[158:159]
	v_pk_mul_f32 v[16:17], v[16:17], v[156:157]

.Lmy_att_skip:
	s_waitcnt vmcnt(0)
	s_branch .LBB0_964
